# v24 + M7 epilogue: all 32 gate-code loads issued before the first wait (was 12, drain, then 20) with counted per-group waits
# speedup vs baseline: 1.0107x; 1.0020x over previous
; __device__ __forceinline__ unsigned cvt_pk_bf16(float lo, float hi) { f32x2c v = {lo, hi}; bf16x2c b = __builtin_convertvector(v, bf16x2c); return __builtin_bit_cast(unsigned, b); }
; __device__ __forceinline__ float ub0(unsigned w) { return (float)(w & 0xFFu); }
; __device__ __forceinline__ float ub1(unsigned w) { return (float)((w >> 8) & 0xFFu); }
; __device__ __forceinline__ float ub2(unsigned w) { return (float)((w >> 16) & 0xFFu); }
; __device__ __forceinline__ float ub3(unsigned w) { return (float)(w >> 24); }
;     __device__ __forceinline__ void operator()(f32x4 (&acc)[2][2][4][2], const Unit& u, int wr, int wc, int fr, int fq) const {
;         const int row0 = u.pm * BM + wr * 64 + fr, col0 = u.pn * BM + wc * 32 + 8 * fq; const int sg = u.seg; const bool fin = sg == 2;
;         const unsigned char* qn = Q + (size_t)row0 * 6144 + sg * 2048 + col0; const unsigned char* qd = fin ? qn : qn + 2048;
;         u32x2 gn[2][4][2], gd[2][4][2];
;     ...
;         BR_LOAD(0); BR_LOAD(1);
; #pragma unroll
;         for (int ai = 0; ai < 2; ++ai) {
; #pragma unroll
;             for (int m = 0; m < 4; ++m)
; #pragma unroll
;                 for (int bj = 0; bj < 2; ++bj) { const u32x2 a = gn[ai][m][bj], d = gd[ai][m][bj];
;                     const float an[8] = {ub0(a.x), ub1(a.x), ub2(a.x), ub3(a.x), ub0(a.y), ub1(a.y), ub2(a.y), ub3(a.y)};
;                     const float dn[8] = {ub0(d.x), ub1(d.x), ub2(d.x), ub3(d.x), ub0(d.y), ub1(d.y), ub2(d.y), ub3(d.y)};
;                     float f[8];
; #pragma unroll
;                     for (int k = 0; k < 8; ++k) { const float rd = __builtin_amdgcn_rcpf(dn[k]); f[k] = an[k] * (fin ? (1.0f / 255.0f) : rd); }
;                     f32x4 v0 = acc[ai][bj][m][0], v1 = acc[ai][bj][m][1];
;                     v0[0] *= f[0]; v0[1] *= f[1]; v0[2] *= f[2]; v0[3] *= f[3]; v1[0] *= f[4]; v1[1] *= f[5]; v1[2] *= f[6]; v1[3] *= f[7];
;                     acc[ai][bj][m][0] = v0; acc[ai][bj][m][1] = v1;
;                     if (fin) { u32x4 w; w.x = cvt_pk_bf16(v0[0], v0[1]); w.y = cvt_pk_bf16(v0[2], v0[3]); w.z = cvt_pk_bf16(v1[0], v1[1]); w.w = cvt_pk_bf16(v1[2], v1[3]);
;                         *(u32x4*)(MO + (size_t)(row0 + ai * HALF + m * 16) * ld + col0 + bj * HALF) = w; } }
.LBB0_2026:
	s_lshl_b32 s34, s6, 11
	s_ashr_i32 s35, s34, 31
	v_lshl_add_u32 v144, s42, 8, v234
	s_cmp_eq_u32 s6, 2
	v_mov_b64_e32 v[146:147], s[26:27]
	v_lshl_or_b32 v142, s52, 8, v236
	s_cselect_b64 s[40:41], -1, 0
	v_mad_i64_i32 v[146:147], s[42:43], v144, s33, v[146:147]
	s_and_b64 s[42:43], s[40:41], exec
	v_lshl_add_u64 v[146:147], v[146:147], 0, s[34:35]
	v_ashrrev_i32_e32 v143, 31, v142
	s_cselect_b32 s24, 0, 0x800
	s_cmp_lg_u32 s6, 2
	v_lshl_add_u64 v[146:147], v[146:147], 0, v[142:143]
	s_mov_b32 s6, 0x18000
	v_add_co_u32_e32 v150, vcc, s6, v146
	v_lshl_add_u64 v[148:149], v[146:147], 0, s[24:25]
	s_nop 0
	v_addc_co_u32_e32 v151, vcc, 0, v147, vcc
	v_add_co_u32_e32 v152, vcc, s6, v148
	s_mov_b32 s6, 0x30000
	s_nop 0
	v_addc_co_u32_e32 v153, vcc, 0, v149, vcc
	global_load_dwordx2 v[238:239], v[146:147], off
	global_load_dwordx2 v[240:241], v[148:149], off
	global_load_dwordx2 v[226:227], v[146:147], off offset:128
	global_load_dwordx2 v[224:225], v[148:149], off offset:128
	global_load_dwordx2 v[220:221], v[150:151], off
	global_load_dwordx2 v[222:223], v[152:153], off
	global_load_dwordx2 v[218:219], v[150:151], off offset:128
	global_load_dwordx2 v[216:217], v[152:153], off offset:128
	v_add_co_u32_e32 v150, vcc, s6, v146
	v_ashrrev_i32_e32 v145, 31, v144
	s_nop 0
	v_addc_co_u32_e32 v151, vcc, 0, v147, vcc
	v_add_co_u32_e32 v152, vcc, s6, v148
	s_mov_b32 s6, 0x48000
	s_nop 0
	v_addc_co_u32_e32 v153, vcc, 0, v149, vcc
	global_load_dwordx2 v[212:213], v[150:151], off
	global_load_dwordx2 v[214:215], v[152:153], off
	global_load_dwordx2 v[210:211], v[150:151], off offset:128
	global_load_dwordx2 v[208:209], v[152:153], off offset:128
	v_add_co_u32_e32 v150, vcc, s6, v146
	v_addc_co_u32_e32 v151, vcc, 0, v147, vcc
	v_add_co_u32_e32 v152, vcc, s6, v148
	s_mov_b32 s6, 0xc0000
	s_nop 0
	v_addc_co_u32_e32 v153, vcc, 0, v149, vcc
	global_load_dwordx2 v[204:205], v[150:151], off
	global_load_dwordx2 v[206:207], v[152:153], off
	global_load_dwordx2 v[202:203], v[150:151], off offset:128
	global_load_dwordx2 v[200:201], v[152:153], off offset:128
	v_add_co_u32_e32 v150, vcc, s6, v146
	s_nop 0
	v_addc_co_u32_e32 v151, vcc, 0, v147, vcc
	v_add_co_u32_e32 v152, vcc, s6, v148
	s_mov_b32 s6, 0xd8000
	s_nop 0
	v_addc_co_u32_e32 v153, vcc, 0, v149, vcc
	global_load_dwordx2 v[196:197], v[150:151], off
	global_load_dwordx2 v[198:199], v[152:153], off
	global_load_dwordx2 v[194:195], v[150:151], off offset:128
	global_load_dwordx2 v[192:193], v[152:153], off offset:128
	v_add_co_u32_e32 v150, vcc, s6, v146
	s_nop 0
	v_addc_co_u32_e32 v151, vcc, 0, v147, vcc
	v_add_co_u32_e32 v152, vcc, s6, v148
	s_mov_b32 s6, 0xf0000
	s_nop 0
	v_addc_co_u32_e32 v153, vcc, 0, v149, vcc
	global_load_dwordx2 v[188:189], v[150:151], off
	global_load_dwordx2 v[190:191], v[152:153], off
	global_load_dwordx2 v[186:187], v[150:151], off offset:128
	global_load_dwordx2 v[162:163], v[152:153], off offset:128
	v_add_co_u32_e32 v150, vcc, s6, v146
	s_nop 0
	v_addc_co_u32_e32 v151, vcc, 0, v147, vcc
	v_add_co_u32_e32 v152, vcc, s6, v148
	s_mov_b32 s6, 0x108000
	s_nop 0
	v_addc_co_u32_e32 v153, vcc, 0, v149, vcc
	v_add_co_u32_e32 v146, vcc, s6, v146
	global_load_dwordx2 v[158:159], v[150:151], off
	s_nop 0
	v_addc_co_u32_e32 v147, vcc, 0, v147, vcc
	v_add_co_u32_e32 v242, vcc, s6, v148
	global_load_dwordx2 v[160:161], v[152:153], off
	global_load_dwordx2 v[156:157], v[150:151], off offset:128
	global_load_dwordx2 v[154:155], v[152:153], off offset:128
	v_addc_co_u32_e32 v243, vcc, 0, v149, vcc
	global_load_dwordx2 v[150:151], v[146:147], off
	global_load_dwordx2 v[152:153], v[242:243], off
	global_load_dwordx2 v[148:149], v[146:147], off offset:128
	s_nop 0
	global_load_dwordx2 v[146:147], v[242:243], off offset:128
	s_waitcnt vmcnt(30)
	v_cvt_f32_ubyte2_e32 v244, v238
	v_cvt_f32_ubyte0_e32 v248, v240
	v_cvt_f32_ubyte1_e32 v249, v240
	v_cvt_f32_ubyte2_e32 v250, v240
	v_cvt_f32_ubyte3_e32 v240, v240
	v_rcp_iflag_f32_e32 v240, v240
	v_cvt_f32_ubyte0_e32 v242, v238
	v_cvt_f32_ubyte1_e32 v243, v238
	v_cvt_f32_ubyte3_e32 v238, v238
	v_cvt_f32_ubyte0_e32 v251, v241
	v_cndmask_b32_e64 v240, v240, v233, s[40:41]
	v_rcp_iflag_f32_e32 v248, v248
	v_mul_f32_e32 v238, v240, v238
	v_rcp_iflag_f32_e32 v240, v251
	v_cvt_f32_ubyte0_e32 v245, v239
	v_cvt_f32_ubyte1_e32 v252, v241
	v_cndmask_b32_e64 v248, v248, v233, s[40:41]
	v_cndmask_b32_e64 v240, v240, v233, s[40:41]
	v_mul_f32_e32 v242, v248, v242
	v_rcp_iflag_f32_e32 v248, v249
	v_mul_f32_e32 v240, v240, v245
	v_rcp_iflag_f32_e32 v245, v252
	v_cvt_f32_ubyte1_e32 v246, v239
	v_cvt_f32_ubyte2_e32 v253, v241
	v_cvt_f32_ubyte3_e32 v241, v241
	v_cndmask_b32_e64 v248, v248, v233, s[40:41]
	v_cndmask_b32_e64 v245, v245, v233, s[40:41]
	v_mul_f32_e32 v243, v248, v243
	v_rcp_iflag_f32_e32 v248, v250
	v_mul_f32_e32 v245, v245, v246
	v_rcp_iflag_f32_e32 v246, v253
	v_rcp_iflag_f32_e32 v241, v241
	v_cvt_f32_ubyte2_e32 v247, v239
	v_cvt_f32_ubyte3_e32 v239, v239
	v_cndmask_b32_e64 v248, v248, v233, s[40:41]
	v_cndmask_b32_e64 v246, v246, v233, s[40:41]
	v_cndmask_b32_e64 v241, v241, v233, s[40:41]
	v_mul_f32_e32 v244, v248, v244
	v_mul_f32_e32 v246, v246, v247
	v_mul_f32_e32 v239, v241, v239
	v_mul_f32_e32 v128, v128, v242
	v_mul_f32_e32 v129, v129, v243
	v_mul_f32_e32 v130, v130, v244
	v_mul_f32_e32 v131, v131, v238
	v_mul_f32_e32 v124, v124, v240
	v_mul_f32_e32 v125, v125, v245
	v_mul_f32_e32 v126, v126, v246
	v_mul_f32_e32 v127, v127, v239
	s_cbranch_scc1 .LBB0_2028
	v_lshlrev_b64 v[242:243], 12, v[144:145]
	v_lshl_add_u64 v[242:243], s[28:29], 0, v[242:243]
	v_cvt_pk_bf16_f32 v238, v128, v129
	v_cvt_pk_bf16_f32 v239, v130, v131
	v_cvt_pk_bf16_f32 v240, v124, v125
	v_cvt_pk_bf16_f32 v241, v126, v127
	v_lshl_add_u64 v[242:243], v[142:143], 1, v[242:243]
	global_store_dwordx4 v[242:243], v[238:241], off sc0 sc1
; __device__ __forceinline__ float ub0(unsigned w) { return (float)(w & 0xFFu); }
; __device__ __forceinline__ float ub1(unsigned w) { return (float)((w >> 8) & 0xFFu); }
; __device__ __forceinline__ float ub2(unsigned w) { return (float)((w >> 16) & 0xFFu); }
; __device__ __forceinline__ float ub3(unsigned w) { return (float)(w >> 24); }
;     __device__ __forceinline__ void operator()(f32x4 (&acc)[2][2][4][2], const Unit& u, int wr, int wc, int fr, int fq) const {
;     ...
;                 for (int bj = 0; bj < 2; ++bj) { const u32x2 a = gn[ai][m][bj], d = gd[ai][m][bj];
;                     const float an[8] = {ub0(a.x), ub1(a.x), ub2(a.x), ub3(a.x), ub0(a.y), ub1(a.y), ub2(a.y), ub3(a.y)};
;                     const float dn[8] = {ub0(d.x), ub1(d.x), ub2(d.x), ub3(d.x), ub0(d.y), ub1(d.y), ub2(d.y), ub3(d.y)};
;                     float f[8];
; #pragma unroll
;                     for (int k = 0; k < 8; ++k) { const float rd = __builtin_amdgcn_rcpf(dn[k]); f[k] = an[k] * (fin ? (1.0f / 255.0f) : rd); }
;                     f32x4 v0 = acc[ai][bj][m][0], v1 = acc[ai][bj][m][1];
;                     v0[0] *= f[0]; v0[1] *= f[1]; v0[2] *= f[2]; v0[3] *= f[3]; v1[0] *= f[4]; v1[1] *= f[5]; v1[2] *= f[6]; v1[3] *= f[7];
;                     acc[ai][bj][m][0] = v0; acc[ai][bj][m][1] = v1;
.LBB0_2028:
	s_waitcnt vmcnt(28)
	s_cmp_lg_u64 s[40:41], 0
	s_cbranch_scc1 .Lm7f_0
	v_cvt_f32_ubyte0_e32 v238, v227
	v_cvt_f32_ubyte1_e32 v239, v227
	v_cvt_f32_ubyte2_e32 v240, v227
	v_cvt_f32_ubyte3_e32 v241, v227
	v_cvt_f32_ubyte0_e32 v242, v226
	v_cvt_f32_ubyte1_e32 v243, v226
	v_cvt_f32_ubyte2_e32 v244, v226
	v_cvt_f32_ubyte3_e32 v245, v226
	v_cvt_f32_ubyte0_e32 v246, v225
	v_cvt_f32_ubyte1_e32 v247, v225
	v_cvt_f32_ubyte2_e32 v248, v225
	v_cvt_f32_ubyte3_e32 v249, v225
	v_cvt_f32_ubyte0_e32 v250, v224
	v_cvt_f32_ubyte1_e32 v251, v224
	v_cvt_f32_ubyte2_e32 v252, v224
	v_cvt_f32_ubyte3_e32 v253, v224
	v_rcp_iflag_f32_e32 v246, v246
	v_rcp_iflag_f32_e32 v247, v247
	v_rcp_iflag_f32_e32 v248, v248
	v_rcp_iflag_f32_e32 v249, v249
	v_rcp_iflag_f32_e32 v250, v250
	v_rcp_iflag_f32_e32 v251, v251
	v_rcp_iflag_f32_e32 v252, v252
	v_rcp_iflag_f32_e32 v253, v253
	v_pk_mul_f32 v[238:239], v[238:239], v[246:247]
	v_pk_mul_f32 v[240:241], v[240:241], v[248:249]
	v_pk_mul_f32 v[242:243], v[242:243], v[250:251]
	v_pk_mul_f32 v[244:245], v[244:245], v[252:253]
	v_pk_mul_f32 v[92:93], v[92:93], v[238:239]
	v_pk_mul_f32 v[94:95], v[94:95], v[240:241]
	v_pk_mul_f32 v[96:97], v[96:97], v[242:243]
	v_pk_mul_f32 v[98:99], v[98:99], v[244:245]
	v_cndmask_b32_e64 v224, 0, 1, s[40:41]
	v_cmp_ne_u32_e64 s[42:43], 1, v224
	s_branch .LBB0_2030

; __device__ __forceinline__ float ub0(unsigned w) { return (float)(w & 0xFFu); }
; __device__ __forceinline__ float ub1(unsigned w) { return (float)((w >> 8) & 0xFFu); }
; __device__ __forceinline__ float ub2(unsigned w) { return (float)((w >> 16) & 0xFFu); }
; __device__ __forceinline__ float ub3(unsigned w) { return (float)(w >> 24); }
;     __device__ __forceinline__ void operator()(f32x4 (&acc)[2][2][4][2], const Unit& u, int wr, int wc, int fr, int fq) const {
;     ...
;                 for (int bj = 0; bj < 2; ++bj) { const u32x2 a = gn[ai][m][bj], d = gd[ai][m][bj];
;                     const float an[8] = {ub0(a.x), ub1(a.x), ub2(a.x), ub3(a.x), ub0(a.y), ub1(a.y), ub2(a.y), ub3(a.y)};
;                     const float dn[8] = {ub0(d.x), ub1(d.x), ub2(d.x), ub3(d.x), ub0(d.y), ub1(d.y), ub2(d.y), ub3(d.y)};
;                     float f[8];
; #pragma unroll
;                     for (int k = 0; k < 8; ++k) { const float rd = __builtin_amdgcn_rcpf(dn[k]); f[k] = an[k] * (fin ? (1.0f / 255.0f) : rd); }
;                     f32x4 v0 = acc[ai][bj][m][0], v1 = acc[ai][bj][m][1];
;                     v0[0] *= f[0]; v0[1] *= f[1]; v0[2] *= f[2]; v0[3] *= f[3]; v1[0] *= f[4]; v1[1] *= f[5]; v1[2] *= f[6]; v1[3] *= f[7];
.LBB0_2030:
	s_waitcnt vmcnt(26)
	s_cmp_lg_u64 s[40:41], 0
	s_cbranch_scc1 .Lm7f_1
	v_cvt_f32_ubyte0_e32 v238, v221
	v_cvt_f32_ubyte1_e32 v239, v221
	v_cvt_f32_ubyte2_e32 v240, v221
	v_cvt_f32_ubyte3_e32 v241, v221
	v_cvt_f32_ubyte0_e32 v242, v220
	v_cvt_f32_ubyte1_e32 v243, v220
	v_cvt_f32_ubyte2_e32 v244, v220
	v_cvt_f32_ubyte3_e32 v245, v220
	v_cvt_f32_ubyte0_e32 v246, v223
	v_cvt_f32_ubyte1_e32 v247, v223
	v_cvt_f32_ubyte2_e32 v248, v223
	v_cvt_f32_ubyte3_e32 v249, v223
	v_cvt_f32_ubyte0_e32 v250, v222
	v_cvt_f32_ubyte1_e32 v251, v222
	v_cvt_f32_ubyte2_e32 v252, v222
	v_cvt_f32_ubyte3_e32 v253, v222
	v_rcp_iflag_f32_e32 v246, v246
	v_rcp_iflag_f32_e32 v247, v247
	v_rcp_iflag_f32_e32 v248, v248
	v_rcp_iflag_f32_e32 v249, v249
	v_rcp_iflag_f32_e32 v250, v250
	v_rcp_iflag_f32_e32 v251, v251
	v_rcp_iflag_f32_e32 v252, v252
	v_rcp_iflag_f32_e32 v253, v253
	v_pk_mul_f32 v[238:239], v[238:239], v[246:247]
	v_pk_mul_f32 v[240:241], v[240:241], v[248:249]
	v_pk_mul_f32 v[242:243], v[242:243], v[250:251]
	v_pk_mul_f32 v[244:245], v[244:245], v[252:253]
	v_pk_mul_f32 v[116:117], v[116:117], v[238:239]
	v_pk_mul_f32 v[118:119], v[118:119], v[240:241]
	v_pk_mul_f32 v[120:121], v[120:121], v[242:243]
	v_pk_mul_f32 v[122:123], v[122:123], v[244:245]
	v_or_b32_e32 v224, 16, v144
	v_ashrrev_i32_e32 v225, 31, v224
	s_branch .LBB0_2032

; __device__ __forceinline__ float ub0(unsigned w) { return (float)(w & 0xFFu); }
; __device__ __forceinline__ float ub1(unsigned w) { return (float)((w >> 8) & 0xFFu); }
; __device__ __forceinline__ float ub2(unsigned w) { return (float)((w >> 16) & 0xFFu); }
; __device__ __forceinline__ float ub3(unsigned w) { return (float)(w >> 24); }
;     __device__ __forceinline__ void operator()(f32x4 (&acc)[2][2][4][2], const Unit& u, int wr, int wc, int fr, int fq) const {
;     ...
;                 for (int bj = 0; bj < 2; ++bj) { const u32x2 a = gn[ai][m][bj], d = gd[ai][m][bj];
;                     const float an[8] = {ub0(a.x), ub1(a.x), ub2(a.x), ub3(a.x), ub0(a.y), ub1(a.y), ub2(a.y), ub3(a.y)};
;                     const float dn[8] = {ub0(d.x), ub1(d.x), ub2(d.x), ub3(d.x), ub0(d.y), ub1(d.y), ub2(d.y), ub3(d.y)};
;                     float f[8];
; #pragma unroll
;                     for (int k = 0; k < 8; ++k) { const float rd = __builtin_amdgcn_rcpf(dn[k]); f[k] = an[k] * (fin ? (1.0f / 255.0f) : rd); }
;                     f32x4 v0 = acc[ai][bj][m][0], v1 = acc[ai][bj][m][1];
;                     v0[0] *= f[0]; v0[1] *= f[1]; v0[2] *= f[2]; v0[3] *= f[3]; v1[0] *= f[4]; v1[1] *= f[5]; v1[2] *= f[6]; v1[3] *= f[7];
.LBB0_2032:
	s_waitcnt vmcnt(24)
	s_cmp_lg_u64 s[40:41], 0
	s_cbranch_scc1 .Lm7f_2
	v_cvt_f32_ubyte0_e32 v238, v219
	v_cvt_f32_ubyte1_e32 v239, v219
	v_cvt_f32_ubyte2_e32 v240, v219
	v_cvt_f32_ubyte3_e32 v241, v219
	v_cvt_f32_ubyte0_e32 v242, v218
	v_cvt_f32_ubyte1_e32 v243, v218
	v_cvt_f32_ubyte2_e32 v244, v218
	v_cvt_f32_ubyte3_e32 v245, v218
	v_cvt_f32_ubyte0_e32 v246, v217
	v_cvt_f32_ubyte1_e32 v247, v217
	v_cvt_f32_ubyte2_e32 v248, v217
	v_cvt_f32_ubyte3_e32 v249, v217
	v_cvt_f32_ubyte0_e32 v250, v216
	v_cvt_f32_ubyte1_e32 v251, v216
	v_cvt_f32_ubyte2_e32 v252, v216
	v_cvt_f32_ubyte3_e32 v253, v216
	v_rcp_iflag_f32_e32 v246, v246
	v_rcp_iflag_f32_e32 v247, v247
	v_rcp_iflag_f32_e32 v248, v248
	v_rcp_iflag_f32_e32 v249, v249
	v_rcp_iflag_f32_e32 v250, v250
	v_rcp_iflag_f32_e32 v251, v251
	v_rcp_iflag_f32_e32 v252, v252
	v_rcp_iflag_f32_e32 v253, v253
	v_pk_mul_f32 v[238:239], v[238:239], v[246:247]
	v_pk_mul_f32 v[240:241], v[240:241], v[248:249]
	v_pk_mul_f32 v[242:243], v[242:243], v[250:251]
	v_pk_mul_f32 v[244:245], v[244:245], v[252:253]
	v_pk_mul_f32 v[84:85], v[84:85], v[238:239]
	v_pk_mul_f32 v[86:87], v[86:87], v[240:241]
	v_pk_mul_f32 v[88:89], v[88:89], v[242:243]
	v_pk_mul_f32 v[90:91], v[90:91], v[244:245]
	s_branch .LBB0_2034

; __device__ __forceinline__ float ub0(unsigned w) { return (float)(w & 0xFFu); }
; __device__ __forceinline__ float ub1(unsigned w) { return (float)((w >> 8) & 0xFFu); }
; __device__ __forceinline__ float ub2(unsigned w) { return (float)((w >> 16) & 0xFFu); }
; __device__ __forceinline__ float ub3(unsigned w) { return (float)(w >> 24); }
;     __device__ __forceinline__ void operator()(f32x4 (&acc)[2][2][4][2], const Unit& u, int wr, int wc, int fr, int fq) const {
;     ...
;                 for (int bj = 0; bj < 2; ++bj) { const u32x2 a = gn[ai][m][bj], d = gd[ai][m][bj];
;                     const float an[8] = {ub0(a.x), ub1(a.x), ub2(a.x), ub3(a.x), ub0(a.y), ub1(a.y), ub2(a.y), ub3(a.y)};
;                     const float dn[8] = {ub0(d.x), ub1(d.x), ub2(d.x), ub3(d.x), ub0(d.y), ub1(d.y), ub2(d.y), ub3(d.y)};
;                     float f[8];
; #pragma unroll
;                     for (int k = 0; k < 8; ++k) { const float rd = __builtin_amdgcn_rcpf(dn[k]); f[k] = an[k] * (fin ? (1.0f / 255.0f) : rd); }
;                     f32x4 v0 = acc[ai][bj][m][0], v1 = acc[ai][bj][m][1];
;                     v0[0] *= f[0]; v0[1] *= f[1]; v0[2] *= f[2]; v0[3] *= f[3]; v1[0] *= f[4]; v1[1] *= f[5]; v1[2] *= f[6]; v1[3] *= f[7];
.LBB0_2034:
	s_waitcnt vmcnt(22)
	s_cmp_lg_u64 s[40:41], 0
	s_cbranch_scc1 .Lm7f_3
	v_cvt_f32_ubyte0_e32 v238, v213
	v_cvt_f32_ubyte1_e32 v239, v213
	v_cvt_f32_ubyte2_e32 v240, v213
	v_cvt_f32_ubyte3_e32 v241, v213
	v_cvt_f32_ubyte0_e32 v242, v212
	v_cvt_f32_ubyte1_e32 v243, v212
	v_cvt_f32_ubyte2_e32 v244, v212
	v_cvt_f32_ubyte3_e32 v245, v212
	v_cvt_f32_ubyte0_e32 v246, v215
	v_cvt_f32_ubyte1_e32 v247, v215
	v_cvt_f32_ubyte2_e32 v248, v215
	v_cvt_f32_ubyte3_e32 v249, v215
	v_cvt_f32_ubyte0_e32 v250, v214
	v_cvt_f32_ubyte1_e32 v251, v214
	v_cvt_f32_ubyte2_e32 v252, v214
	v_cvt_f32_ubyte3_e32 v253, v214
	v_rcp_iflag_f32_e32 v246, v246
	v_rcp_iflag_f32_e32 v247, v247
	v_rcp_iflag_f32_e32 v248, v248
	v_rcp_iflag_f32_e32 v249, v249
	v_rcp_iflag_f32_e32 v250, v250
	v_rcp_iflag_f32_e32 v251, v251
	v_rcp_iflag_f32_e32 v252, v252
	v_rcp_iflag_f32_e32 v253, v253
	v_pk_mul_f32 v[238:239], v[238:239], v[246:247]
	v_pk_mul_f32 v[240:241], v[240:241], v[248:249]
	v_pk_mul_f32 v[242:243], v[242:243], v[250:251]
	v_pk_mul_f32 v[244:245], v[244:245], v[252:253]
	v_pk_mul_f32 v[108:109], v[108:109], v[238:239]
	v_pk_mul_f32 v[110:111], v[110:111], v[240:241]
	v_pk_mul_f32 v[112:113], v[112:113], v[242:243]
	v_pk_mul_f32 v[114:115], v[114:115], v[244:245]
	v_or_b32_e32 v216, 32, v144
	v_ashrrev_i32_e32 v217, 31, v216
	s_branch .LBB0_2036

; __device__ __forceinline__ float ub0(unsigned w) { return (float)(w & 0xFFu); }
; __device__ __forceinline__ float ub1(unsigned w) { return (float)((w >> 8) & 0xFFu); }
; __device__ __forceinline__ float ub2(unsigned w) { return (float)((w >> 16) & 0xFFu); }
; __device__ __forceinline__ float ub3(unsigned w) { return (float)(w >> 24); }
;     __device__ __forceinline__ void operator()(f32x4 (&acc)[2][2][4][2], const Unit& u, int wr, int wc, int fr, int fq) const {
;     ...
;                 for (int bj = 0; bj < 2; ++bj) { const u32x2 a = gn[ai][m][bj], d = gd[ai][m][bj];
;                     const float an[8] = {ub0(a.x), ub1(a.x), ub2(a.x), ub3(a.x), ub0(a.y), ub1(a.y), ub2(a.y), ub3(a.y)};
;                     const float dn[8] = {ub0(d.x), ub1(d.x), ub2(d.x), ub3(d.x), ub0(d.y), ub1(d.y), ub2(d.y), ub3(d.y)};
;                     float f[8];
; #pragma unroll
;                     for (int k = 0; k < 8; ++k) { const float rd = __builtin_amdgcn_rcpf(dn[k]); f[k] = an[k] * (fin ? (1.0f / 255.0f) : rd); }
;                     f32x4 v0 = acc[ai][bj][m][0], v1 = acc[ai][bj][m][1];
;                     v0[0] *= f[0]; v0[1] *= f[1]; v0[2] *= f[2]; v0[3] *= f[3]; v1[0] *= f[4]; v1[1] *= f[5]; v1[2] *= f[6]; v1[3] *= f[7];
.LBB0_2036:
	s_waitcnt vmcnt(20)
	s_cmp_lg_u64 s[40:41], 0
	s_cbranch_scc1 .Lm7f_4
	v_cvt_f32_ubyte0_e32 v238, v211
	v_cvt_f32_ubyte1_e32 v239, v211
	v_cvt_f32_ubyte2_e32 v240, v211
	v_cvt_f32_ubyte3_e32 v241, v211
	v_cvt_f32_ubyte0_e32 v242, v210
	v_cvt_f32_ubyte1_e32 v243, v210
	v_cvt_f32_ubyte2_e32 v244, v210
	v_cvt_f32_ubyte3_e32 v245, v210
	v_cvt_f32_ubyte0_e32 v246, v209
	v_cvt_f32_ubyte1_e32 v247, v209
	v_cvt_f32_ubyte2_e32 v248, v209
	v_cvt_f32_ubyte3_e32 v249, v209
	v_cvt_f32_ubyte0_e32 v250, v208
	v_cvt_f32_ubyte1_e32 v251, v208
	v_cvt_f32_ubyte2_e32 v252, v208
	v_cvt_f32_ubyte3_e32 v253, v208
	v_rcp_iflag_f32_e32 v246, v246
	v_rcp_iflag_f32_e32 v247, v247
	v_rcp_iflag_f32_e32 v248, v248
	v_rcp_iflag_f32_e32 v249, v249
	v_rcp_iflag_f32_e32 v250, v250
	v_rcp_iflag_f32_e32 v251, v251
	v_rcp_iflag_f32_e32 v252, v252
	v_rcp_iflag_f32_e32 v253, v253
	v_pk_mul_f32 v[238:239], v[238:239], v[246:247]
	v_pk_mul_f32 v[240:241], v[240:241], v[248:249]
	v_pk_mul_f32 v[242:243], v[242:243], v[250:251]
	v_pk_mul_f32 v[244:245], v[244:245], v[252:253]
	v_pk_mul_f32 v[76:77], v[76:77], v[238:239]
	v_pk_mul_f32 v[78:79], v[78:79], v[240:241]
	v_pk_mul_f32 v[80:81], v[80:81], v[242:243]
	v_pk_mul_f32 v[82:83], v[82:83], v[244:245]
	s_branch .LBB0_2038
